# v046 with smaller per-tail conversion shares (sized for the slower in-tail conversion rate), P0 skips the hidden item ranges
# baseline (speedup 1.0000x reference)
.LBB0_31:
	v_mov_b32_e32 v1, v0
	s_barrier
	s_mov_b32 s8, s87
	s_mov_b32 s14, s88
	s_mov_b32 s99, 0
	s_mov_b32 s100, 0xb03f
	s_mov_b32 s101, 0

.LBB0_34:
	s_cmp_lg_u32 s101, 0
	s_cbranch_scc1 .Lc0_go
	s_cmp_lt_i32 s15, 19008
	s_cbranch_scc1 .Lc0_go
	s_cmp_lt_i32 s15, 22720
	s_cbranch_scc1 .LBB0_33
	s_cmp_lt_i32 s15, 26176
	s_cbranch_scc1 .Lc0_go
	s_cmp_lt_i32 s15, 36928
	s_cbranch_scc1 .LBB0_33

.LBB0_268:
	v_readlane_b32 s14, v252, 2
	v_mov_b32_e32 v1, v0
	s_cmp_lt_u32 s14, 24
	s_cbranch_scc1 .Lret_c3
	s_sub_u32 s14, s14, 24
	s_movk_i32 s8, 232
	s_mov_b32 s9, 0
	s_mov_b32 s99, 19008
	s_mov_b32 s100, 22719
	s_mov_b32 s101, 1
	s_branch .Lconv0_entry

.LBB0_997:
	v_readlane_b32 s14, v252, 2
	v_mov_b32_e32 v1, v0
	s_cmp_lt_u32 s14, 64
	s_cbranch_scc1 .Lret_c7
	s_sub_u32 s14, s14, 64
	s_movk_i32 s8, 192
	s_mov_b32 s9, 0
	s_mov_b32 s99, 26176
	s_mov_b32 s100, 36927
	s_mov_b32 s101, 2
	s_branch .Lconv0_entry

.LBB0_1076:
	v_readlane_b32 s13, v252, 2
	v_mov_b32_e32 v1, v0
	s_cmp_lt_u32 s13, 64
	s_cbranch_scc1 .Lret_c8
	s_sub_u32 s13, s13, 64
	s_movk_i32 s12, 192
	s_mov_b32 s22, 0
	s_mov_b32 s99, 0
	s_mov_b32 s100, 1535
	s_mov_b32 s101, 3
	s_branch .Lconv1_entry

.LBB0_1263:
	v_readlane_b32 s13, v252, 2
	v_mov_b32_e32 v1, v0
	s_cmp_lt_u32 s13, 96
	s_cbranch_scc1 .Lret_c10
	s_sub_u32 s13, s13, 96
	s_movk_i32 s12, 160
	s_mov_b32 s22, 0
	s_mov_b32 s99, 1536
	s_mov_b32 s100, 6655
	s_mov_b32 s101, 4
	s_branch .Lconv1_entry

.LBB0_1411:
	v_readlane_b32 s13, v252, 2
	v_mov_b32_e32 v1, v0
	s_cmp_lt_u32 s13, 64
	s_cbranch_scc1 .Lret_c12
	s_sub_u32 s13, s13, 64
	s_movk_i32 s12, 192
	s_mov_b32 s22, 0
	s_mov_b32 s99, 6656
	s_mov_b32 s100, 18943
	s_mov_b32 s101, 5
	s_branch .Lconv1_entry

.LBB0_1492:
	v_mov_b32_e32 v1, v0
	s_barrier
	s_mov_b32 s12, s87
	s_mov_b32 s13, s88
	s_mov_b32 s99, 18944
	s_mov_b32 s100, 0xb03f
	s_mov_b32 s101, 0
